# all of WF1 transposition moved into idle-CU windows (GLU 2 per wave, G2 exit, G3 exit); norm2 phase converts nothing
# baseline (speedup 1.0000x reference)
; __device__ __forceinline__ int opaque_tid() { int t = threadIdx.x; asm volatile("" : "+v"(t)); return t; }
; #define PH(b) if ((PHM >> (b)) & 1)
; #define PHASE_BEGIN unsigned char* ws = opaque_ptr(P.ws); const int z = opaque_zero(); (void)ws; (void)z;
; __global__ void __launch_bounds__(512, 2) mega_fwd(Params P) {
;     ...
;         for (int rep_ = 0; rep_ < ((PROBE_DUP & 32) ? 2 : 1); ++rep_) PH(1) { PHASE_BEGIN
;             const int tid = opaque_tid(), lane = tid & 63, wave = __builtin_amdgcn_readfirstlane(tid >> 6); const int gw = c * 8 + wave, NGW = (G + z) * 8;
;             const float* wf1 = PIN(I_WF1) + (size_t)l * D * 2 * DFF; const float* wf2 = PIN(I_WF2) + (size_t)l * DFF * D;
;             const int n1 = 32 * 44, n2 = 88 * 8;
;             { const int tot4 = (n1 + n2) * 4; const int s0 = (int)((unsigned)(gw * tot4) / (unsigned)NGW), s1 = (int)((unsigned)((gw + 1) * tot4) / (unsigned)NGW);
;             for (int ss = s0; ss < s1; ++ss) {
;                 const int it = ss >> 2, sub = ss & 3;
;                 if (it < n1) transpose_item<1>(wf1, D, 2 * DFF, WF1, it, sub, lane);
;                 else transpose_item<0>(wf2, DFF, D, WF2, it - n1, sub, lane);
;             } }
.Lscan2_ret:
	s_mov_b64 exec, -1
	s_waitcnt vmcnt(0) lgkmcnt(0)
	s_movk_i32 s73, 0x2000
	s_movk_i32 s100, 0x7e
	s_sub_u32 s101, s2, 0x82
	s_lshl_b32 s101, s101, 3
	s_mov_b32 s4, 0x7e0
	v_writelane_b32 v255, s4, 50
	s_nop 1
	s_mov_b32 s4, 0x0
	v_writelane_b32 v255, s4, 51
	s_nop 1
	s_mov_b32 s4, 0x2
	v_writelane_b32 v255, s4, 53
	s_nop 1
	s_branch .Lw2_entry

; #define PH(b) if ((PHM >> (b)) & 1)
; #define PHASE_BEGIN unsigned char* ws = opaque_ptr(P.ws); const int z = opaque_zero(); (void)ws; (void)z;
; #define GSYNC() xcd_barrier(xbar)
; __global__ void __launch_bounds__(512, 2) mega_fwd(Params P) {
;     ...
;         PH(10) { PHASE_BEGIN
;           pg8::BranchOrder S{P5, WBR, LDP, 1024, MP / 256, 8, G, c, 16, 4}; pg8::EpiG2 E{GT, (u32x4*)(ws + WS_XH) + (size_t)c * 16 * 512, HB, PART2, 4};
;           pg8::gemm_phase(lds, LDP, 1024, S, E); }
;         GSYNC();
.LBB0_1297:
	s_waitcnt vmcnt(0)
	v_readlane_b32 s94, v254, 36
	v_readlane_b32 s96, v254, 38
	v_readlane_b32 s90, v254, 40
	v_readlane_b32 s88, v254, 42
	v_readlane_b32 s92, v254, 44
	v_readlane_b32 s74, v254, 46
	v_readlane_b32 s95, v254, 37
	v_readlane_b32 s97, v254, 39
	v_readlane_b32 s91, v254, 41
	v_readlane_b32 s89, v254, 43
	v_readlane_b32 s93, v254, 45
	v_readlane_b32 s75, v254, 47
	s_movk_i32 s71, 0x1ff
	s_barrier
	s_cmpk_lt_u32 s2, 0x60
	s_cbranch_scc1 .Lw2_skip_g2
	v_writelane_b32 v255, s0, 8
	s_nop 1
	v_writelane_b32 v255, s1, 9
	s_nop 1
	v_writelane_b32 v255, s4, 10
	s_nop 1
	v_writelane_b32 v255, s5, 11
	s_nop 1
	v_writelane_b32 v255, s14, 12
	s_nop 1
	v_writelane_b32 v255, s15, 13
	s_nop 1
	v_writelane_b32 v255, s16, 14
	s_nop 1
	v_writelane_b32 v255, s17, 15
	s_nop 1
	v_writelane_b32 v255, s18, 16
	s_nop 1
	v_writelane_b32 v255, s19, 17
	s_nop 1
	v_writelane_b32 v255, s24, 18
	s_nop 1
	v_writelane_b32 v255, s25, 19
	s_nop 1
	v_writelane_b32 v255, s28, 20
	s_nop 1
	v_writelane_b32 v255, s29, 21
	s_nop 1
	v_writelane_b32 v255, s30, 22
	s_nop 1
	v_writelane_b32 v255, s31, 23
	s_nop 1
	v_writelane_b32 v255, s68, 24
	s_nop 1
	v_writelane_b32 v255, s73, 25
	s_nop 1
	s_movk_i32 s73, 0x2000
	s_movk_i32 s100, 0xa0
	s_sub_u32 s101, s2, 0x60
	s_lshl_b32 s101, s101, 3
	s_mov_b32 s4, 0x500
	v_writelane_b32 v255, s4, 50
	s_nop 1
	s_mov_b32 s4, 0x7e0
	v_writelane_b32 v255, s4, 51
	s_nop 1
	s_mov_b32 s4, 0x3
	v_writelane_b32 v255, s4, 53
	s_nop 1
	s_branch .Lw2_entry

; #define PH(b) if ((PHM >> (b)) & 1)
; #define PHASE_BEGIN unsigned char* ws = opaque_ptr(P.ws); const int z = opaque_zero(); (void)ws; (void)z;
; #define GSYNC() xcd_barrier(xbar)
; __global__ void __launch_bounds__(512, 2) mega_fwd(Params P) {
;     ...
;         PH(11) { PHASE_BEGIN
;           pg8::SplitOrder S{HB, WOUT, D, D, MP / 256, 8, G, c, D / 64, 4, 8}; pg8::EpiMix E{MIX, D, PART, 4};
;           pg8::gemm_phase(lds, D, D, S, E); }
;         GSYNC();
.LBB0_1499:
	s_waitcnt vmcnt(0)
	v_readlane_b32 s90, v254, 40
	v_readlane_b32 s88, v254, 42
	v_readlane_b32 s74, v254, 46
	v_readlane_b32 s91, v254, 41
	v_readlane_b32 s89, v254, 43
	v_readlane_b32 s75, v254, 47
	s_movk_i32 s71, 0x1ff
	s_barrier
	s_cmpk_lt_u32 s2, 0x20
	s_cbranch_scc1 .Lw2_skip_g3
	v_writelane_b32 v255, s0, 8
	s_nop 1
	v_writelane_b32 v255, s1, 9
	s_nop 1
	v_writelane_b32 v255, s4, 10
	s_nop 1
	v_writelane_b32 v255, s5, 11
	s_nop 1
	v_writelane_b32 v255, s14, 12
	s_nop 1
	v_writelane_b32 v255, s15, 13
	s_nop 1
	v_writelane_b32 v255, s16, 14
	s_nop 1
	v_writelane_b32 v255, s17, 15
	s_nop 1
	v_writelane_b32 v255, s18, 16
	s_nop 1
	v_writelane_b32 v255, s19, 17
	s_nop 1
	v_writelane_b32 v255, s24, 18
	s_nop 1
	v_writelane_b32 v255, s25, 19
	s_nop 1
	v_writelane_b32 v255, s28, 20
	s_nop 1
	v_writelane_b32 v255, s29, 21
	s_nop 1
	v_writelane_b32 v255, s30, 22
	s_nop 1
	v_writelane_b32 v255, s31, 23
	s_nop 1
	v_writelane_b32 v255, s68, 24
	s_nop 1
	v_writelane_b32 v255, s73, 25
	s_nop 1
	s_movk_i32 s73, 0x2000
	s_movk_i32 s100, 0xe0
	s_sub_u32 s101, s2, 0x20
	s_lshl_b32 s101, s101, 3
	s_mov_b32 s4, 0x920
	v_writelane_b32 v255, s4, 50
	s_nop 1
	s_mov_b32 s4, 0xce0
	v_writelane_b32 v255, s4, 51
	s_nop 1
	s_mov_b32 s4, 0x4
	v_writelane_b32 v255, s4, 53
	s_nop 1
	s_branch .Lw2_entry

; __device__ __forceinline__ int opaque_tid() { int t = threadIdx.x; asm volatile("" : "+v"(t)); return t; }
; #define PH(b) if ((PHM >> (b)) & 1)
; #define PHASE_BEGIN unsigned char* ws = opaque_ptr(P.ws); const int z = opaque_zero(); (void)ws; (void)z;
; __global__ void __launch_bounds__(512, 2) mega_fwd(Params P) {
;     ...
;         for (int rep_ = 0; rep_ < ((PROBE_DUP & 32) ? 2 : 1); ++rep_) PH(1) { PHASE_BEGIN
;             const int tid = opaque_tid(), lane = tid & 63, wave = __builtin_amdgcn_readfirstlane(tid >> 6); const int gw = c * 8 + wave, NGW = (G + z) * 8;
;             const float* wf1 = PIN(I_WF1) + (size_t)l * D * 2 * DFF; const float* wf2 = PIN(I_WF2) + (size_t)l * DFF * D;
;             const int n1 = 32 * 44, n2 = 88 * 8;
;             { const int tot4 = (n1 + n2) * 4; const int s0 = (int)((unsigned)(gw * tot4) / (unsigned)NGW), s1 = (int)((unsigned)((gw + 1) * tot4) / (unsigned)NGW);
;             for (int ss = s0; ss < s1; ++ss) {
;                 const int it = ss >> 2, sub = ss & 3;
;                 if (it < n1) transpose_item<1>(wf1, D, 2 * DFF, WF1, it, sub, lane);
;                 else transpose_item<0>(wf2, DFF, D, WF2, it - n1, sub, lane);
;             } }
.LBB0_1573:
	v_writelane_b32 v254, s24, 57
	s_nop 1
	v_writelane_b32 v254, s25, 58
	s_or_b64 exec, exec, s[0:1]
	s_mov_b32 s100, s64
	s_mov_b32 s101, s51
	s_mov_b32 s4, 0x0
	v_writelane_b32 v255, s4, 50
	s_nop 1
	s_mov_b32 s4, 0x1600
	v_writelane_b32 v255, s4, 51
	s_nop 1
	s_mov_b32 s4, 0x0
	v_writelane_b32 v255, s4, 53
	s_nop 1
